# P10 and P7 intra-wave sums: ds_bpermute butterfly steps replaced by DPP moves with the same lane pairing (lever: DPP instead of LDS round trips)
# baseline (speedup 1.0000x reference)
.LBB0_45:
	s_or_b64 exec, exec, s[40:41]
	s_waitcnt vmcnt(8)
	v_cvt_f32_f16_sdwa v127, v84 dst_sel:DWORD dst_unused:UNUSED_PAD src0_sel:WORD_1
	v_cvt_f32_f16_e32 v126, v84
	v_cvt_f32_f16_sdwa v129, v76 dst_sel:DWORD dst_unused:UNUSED_PAD src0_sel:WORD_1
	v_cvt_f32_f16_e32 v128, v76
	v_lshlrev_b32_e32 v115, 16, v92
	v_lshlrev_b32_e32 v117, 16, v88
	v_and_b32_e32 v114, 0xffff0000, v92
	v_and_b32_e32 v116, 0xffff0000, v88
	v_pk_add_f32 v[114:115], v[116:117], v[114:115]
	v_and_b32_e32 v117, 0xffff0000, v80
	v_lshlrev_b32_e32 v116, 16, v80
	v_and_b32_e32 v125, 0xffff0000, v72
	v_lshlrev_b32_e32 v124, 16, v72
	v_pk_mul_f32 v[116:117], v[116:117], v[124:125]
	v_pk_add_f32 v[124:125], v[128:129], v[126:127]
	v_pk_mul_f32 v[116:117], v[24:25], v[116:117]
	v_pk_add_f32 v[124:125], v[124:125], -2.0 op_sel_hi:[1,0]
	v_lshlrev_b32_e32 v119, 16, v93
	v_pk_fma_f32 v[124:125], v[28:29], v[124:125], 2.0 op_sel_hi:[1,1,0]
	v_lshlrev_b32_e32 v121, 16, v89
	v_pk_mul_f32 v[116:117], v[116:117], v[124:125]
	v_and_b32_e32 v118, 0xffff0000, v93
	v_and_b32_e32 v120, 0xffff0000, v89
	v_add_f32_e32 v2, 0, v116
	v_add_f32_e32 v2, v117, v2
	v_pk_add_f32 v[116:117], v[120:121], v[118:119]
	v_cvt_f32_f16_sdwa v121, v85 dst_sel:DWORD dst_unused:UNUSED_PAD src0_sel:WORD_1
	v_cvt_f32_f16_e32 v120, v85
	v_cvt_f32_f16_sdwa v85, v77 dst_sel:DWORD dst_unused:UNUSED_PAD src0_sel:WORD_1
	v_cvt_f32_f16_e32 v84, v77
	v_and_b32_e32 v119, 0xffff0000, v81
	v_lshlrev_b32_e32 v118, 16, v81
	v_and_b32_e32 v81, 0xffff0000, v73
	v_lshlrev_b32_e32 v80, 16, v73
	v_pk_add_f32 v[76:77], v[84:85], v[120:121]
	v_pk_mul_f32 v[72:73], v[118:119], v[80:81]
	v_pk_add_f32 v[76:77], v[76:77], -2.0 op_sel_hi:[1,0]
	v_pk_mul_f32 v[72:73], v[26:27], v[72:73]
	v_pk_fma_f32 v[76:77], v[30:31], v[76:77], 2.0 op_sel_hi:[1,1,0]
	v_cvt_f32_f16_sdwa v81, v86 dst_sel:DWORD dst_unused:UNUSED_PAD src0_sel:WORD_1
	v_cvt_f32_f16_e32 v80, v86
	v_cvt_f32_f16_sdwa v85, v78 dst_sel:DWORD dst_unused:UNUSED_PAD src0_sel:WORD_1
	v_cvt_f32_f16_e32 v84, v78
	v_pk_mul_f32 v[72:73], v[72:73], v[76:77]
	v_and_b32_e32 v77, 0xffff0000, v74
	v_add_f32_e32 v2, v72, v2
	v_add_f32_e32 v2, v73, v2
	v_and_b32_e32 v73, 0xffff0000, v82
	v_lshlrev_b32_e32 v72, 16, v82
	v_lshlrev_b32_e32 v76, 16, v74
	v_pk_mul_f32 v[72:73], v[72:73], v[76:77]
	v_pk_add_f32 v[76:77], v[84:85], v[80:81]
	v_pk_mul_f32 v[72:73], v[16:17], v[72:73]
	v_pk_add_f32 v[76:77], v[76:77], -2.0 op_sel_hi:[1,0]
	v_cvt_f32_f16_sdwa v81, v87 dst_sel:DWORD dst_unused:UNUSED_PAD src0_sel:WORD_1
	v_pk_fma_f32 v[76:77], v[20:21], v[76:77], 2.0 op_sel_hi:[1,1,0]
	v_cvt_f32_f16_e32 v80, v87
	v_pk_mul_f32 v[72:73], v[72:73], v[76:77]
	v_cvt_f32_f16_e32 v82, v79
	v_add_f32_e32 v2, v72, v2
	v_add_f32_e32 v2, v73, v2
	v_and_b32_e32 v73, 0xffff0000, v83
	v_lshlrev_b32_e32 v72, 16, v83
	v_cvt_f32_f16_sdwa v83, v79 dst_sel:DWORD dst_unused:UNUSED_PAD src0_sel:WORD_1
	v_and_b32_e32 v77, 0xffff0000, v75
	v_lshlrev_b32_e32 v76, 16, v75
	v_pk_mul_f32 v[72:73], v[72:73], v[76:77]
	v_pk_add_f32 v[74:75], v[82:83], v[80:81]
	v_pk_mul_f32 v[72:73], v[18:19], v[72:73]
	v_pk_add_f32 v[74:75], v[74:75], -2.0 op_sel_hi:[1,0]
	v_add_f32_e32 v0, 0, v115
	v_pk_fma_f32 v[74:75], v[22:23], v[74:75], 2.0 op_sel_hi:[1,1,0]
	v_add_f32_e32 v0, v114, v0
	v_pk_mul_f32 v[72:73], v[72:73], v[74:75]
	v_lshlrev_b32_e32 v89, 16, v94
	v_add_f32_e32 v2, v72, v2
	v_add_f32_e32 v112, v73, v2
	s_nop 1
	v_mov_b32_dpp v122, v112 quad_perm:[1,0,3,2] row_mask:0xf bank_mask:0xf
	v_lshlrev_b32_e32 v93, 16, v90
	v_and_b32_e32 v88, 0xffff0000, v94
	v_and_b32_e32 v92, 0xffff0000, v90
	v_add_f32_e32 v0, v117, v0
	v_lshlrev_b32_e32 v113, 16, v91
	v_lshlrev_b32_e32 v123, 16, v95
	v_add_f32_e32 v0, v116, v0
	v_pk_add_f32 v[72:73], v[92:93], v[88:89]
	s_waitcnt lgkmcnt(0)
	v_pk_add_f32 v[74:75], v[112:113], v[122:123]
	v_add_f32_e32 v0, v73, v0
	v_and_b32_e32 v90, 0xffff0000, v95
	v_and_b32_e32 v94, 0xffff0000, v91
	v_add_f32_e32 v91, v72, v0
	v_mov_b32_e32 v95, v75
	v_pk_add_f32 v[76:77], v[94:95], v[90:91]
	s_nop 1
	v_mov_b32_dpp v80, v74 quad_perm:[2,3,0,1] row_mask:0xf bank_mask:0xf
	v_add_f32_e32 v0, v76, v77
	s_nop 1
	v_mov_b32_dpp v2, v0 quad_perm:[1,0,3,2] row_mask:0xf bank_mask:0xf
	v_pk_mov_b32 v[86:87], v[72:73], v[116:117] op_sel:[1,0]
	v_lshlrev_b32_e32 v106, 16, v71
	v_and_b32_e32 v92, 0xffff0000, v71
	v_and_b32_e32 v71, 0xffff0000, v64
	s_waitcnt lgkmcnt(0)
	v_add_f32_e32 v0, v0, v2
	s_nop 1
	v_mov_b32_dpp v2, v0 quad_perm:[2,3,0,1] row_mask:0xf bank_mask:0xf
	v_lshlrev_b32_e32 v73, 16, v65
	v_and_b32_e32 v91, 0xffff0000, v65
	v_lshlrev_b32_e32 v78, 16, v68
	v_lshlrev_b32_e32 v93, 16, v66
	s_waitcnt lgkmcnt(0)
	v_add_f32_e32 v0, v0, v2
	s_nop 1
	v_mov_b32_dpp v2, v0 row_shl:4 row_mask:0xf bank_mask:0x5
	v_mov_b32_dpp v2, v0 row_shr:4 row_mask:0xf bank_mask:0xa
	v_and_b32_e32 v94, 0xffff0000, v67
	v_and_b32_e32 v68, 0xffff0000, v68
	v_lshlrev_b32_e32 v82, 16, v69
	v_lshlrev_b32_e32 v90, 16, v70
	s_waitcnt lgkmcnt(0)
	v_add_f32_e32 v2, v0, v2
	v_mul_f32_e32 v81, 0x3c800000, v2
	v_fmac_f32_e32 v114, 0xbc800000, v2
	v_fmamk_f32 v8, v2, 0xbc800000, v115
	v_mul_f32_e32 v10, v114, v114
	v_mov_b32_e32 v0, v81
	v_fmac_f32_e32 v10, v8, v8
	v_fmamk_f32 v77, v2, 0xbc800000, v117
	v_pk_add_f32 v[86:87], v[86:87], v[0:1] op_sel_hi:[1,0] neg_lo:[0,1] neg_hi:[0,1]
	v_fmac_f32_e32 v10, v77, v77
	v_pk_mul_f32 v[88:89], v[86:87], v[86:87]
	v_pk_add_f32 v[84:85], v[74:75], v[80:81] neg_lo:[0,1] neg_hi:[0,1]
	v_add_f32_e32 v0, v89, v10
	v_fmac_f32_e32 v72, 0xbc800000, v2
	v_add_f32_e32 v0, v88, v0
	v_mov_b32_e32 v88, v85
	v_mov_b32_e32 v89, v72
	v_pk_mul_f32 v[88:89], v[88:89], v[88:89]
	v_fmac_f32_e32 v76, 0xbc800000, v2
	v_add_f32_e32 v0, v89, v0
	v_add_f32_e32 v0, v88, v0
	v_fmac_f32_e32 v0, v76, v76
	s_nop 1
	v_mov_b32_dpp v2, v0 quad_perm:[1,0,3,2] row_mask:0xf bank_mask:0xf
	v_lshlrev_b32_e32 v10, 16, v64
	v_pk_add_f32 v[64:65], v[74:75], v[80:81]
	s_nop 1
	v_mov_b32_dpp v74, v64 row_shl:4 row_mask:0xf bank_mask:0x5
	v_mov_b32_dpp v74, v64 row_shr:4 row_mask:0xf bank_mask:0xa
	v_and_b32_e32 v80, 0xffff0000, v66
	s_waitcnt lgkmcnt(1)
	v_add_f32_e32 v0, v0, v2
	s_nop 1
	v_mov_b32_dpp v2, v0 quad_perm:[2,3,0,1] row_mask:0xf bank_mask:0xf
	v_lshlrev_b32_e32 v81, 16, v67
	v_and_b32_e32 v88, 0xffff0000, v69
	v_and_b32_e32 v70, 0xffff0000, v70
	s_and_b64 s[0:1], exec, vcc
	s_waitcnt lgkmcnt(0)
	v_add_f32_e32 v0, v0, v2
	s_nop 1
	v_mov_b32_dpp v2, v0 row_shl:4 row_mask:0xf bank_mask:0x5
	v_mov_b32_dpp v2, v0 row_shr:4 row_mask:0xf bank_mask:0xa
	s_or_b64 s[38:39], s[0:1], s[38:39]
	s_waitcnt lgkmcnt(0)
	v_add_f32_e32 v0, v0, v2
	v_fmamk_f32 v0, v0, 0x3c800000, v225
	v_rsq_f32_e32 v75, v0
	s_nop 0
	v_pk_add_f32 v[64:65], v[64:65], v[74:75]
	v_mul_f32_e32 v79, v8, v75
	v_pk_mul_f32 v[66:67], v[84:85], v[74:75]
	v_mov_b32_e32 v102, v64
	v_mov_b32_e32 v65, v67
	v_pk_mul_f32 v[66:67], v[102:103], v[78:79]
	v_mul_f32_e32 v69, v114, v75
	v_add_f32_e32 v0, v4, v67
	v_add_f32_e32 v0, v66, v0
	v_mul_f32_e32 v10, v0, v10
	v_mov_b32_e32 v0, v64
	v_pk_mul_f32 v[66:67], v[0:1], v[68:69]
	v_mul_f32_e32 v83, v77, v75
	v_add_f32_e32 v0, v5, v67
	v_mov_b32_e32 v104, v64
	v_add_f32_e32 v0, v66, v0
	v_pk_mul_f32 v[66:67], v[104:105], v[82:83]
	v_mul_f32_e32 v89, v87, v75
	v_add_f32_e32 v2, v6, v67
	v_add_f32_e32 v2, v66, v2
	v_mul_f32_e32 v68, v2, v73
	v_mov_b32_e32 v2, v64
	v_pk_mul_f32 v[66:67], v[2:3], v[88:89]
	v_mov_b32_e32 v108, v64
	v_add_f32_e32 v2, v7, v67
	v_add_f32_e32 v2, v66, v2
	v_mul_f32_e32 v2, v2, v91
	v_mul_f32_e32 v91, v86, v75
	v_pk_mul_f32 v[66:67], v[108:109], v[90:91]
	v_mul_f32_e32 v0, v0, v71
	v_add_f32_e32 v8, v12, v67
	v_add_f32_e32 v8, v66, v8
	v_mul_f32_e32 v69, v8, v93
	v_mul_f32_e32 v71, v72, v75
	v_mov_b32_e32 v8, v64
	v_pk_mul_f32 v[66:67], v[8:9], v[70:71]
	v_mul_f32_e32 v93, v76, v75
	v_add_f32_e32 v8, v13, v67
	v_add_f32_e32 v8, v66, v8
	v_pk_mul_f32 v[66:67], v[64:65], v[106:107]
	v_mul_f32_e32 v8, v8, v80
	v_add_f32_e32 v65, v14, v67
	v_add_f32_e32 v65, v66, v65
	v_mul_f32_e32 v67, v65, v81
	v_mov_b32_e32 v65, v11
	v_pk_mul_f32 v[64:65], v[64:65], v[92:93]
	v_add_f32_e32 v65, v15, v65
	v_add_f32_e32 v64, v64, v65
	v_mul_f32_e32 v70, v64, v94
	v_cvt_pk_bf16_f32 v64, v10, v0
	v_cvt_pk_bf16_f32 v65, v68, v2
	v_cvt_pk_bf16_f32 v66, v69, v8
	v_cvt_pk_bf16_f32 v67, v67, v70
	global_store_dwordx4 v[100:101], v[64:67], off
	v_lshl_add_u64 v[100:101], v[100:101], 0, s[36:37]
	s_waitcnt vmcnt(1)
	v_mov_b32_e32 v95, v39
	v_mov_b64_e32 v[78:79], v[62:63]
	v_mov_b64_e32 v[76:77], v[60:61]
	v_mov_b32_e32 v88, v32
	v_mov_b32_e32 v89, v33
	v_mov_b32_e32 v90, v34
	v_mov_b32_e32 v91, v35
	v_mov_b32_e32 v92, v36
	v_mov_b32_e32 v93, v37
	v_mov_b32_e32 v94, v38
	v_mov_b32_e32 v80, v40
	v_mov_b32_e32 v81, v41
	v_mov_b32_e32 v82, v42
	v_mov_b32_e32 v83, v43
	v_mov_b32_e32 v72, v44
	v_mov_b32_e32 v73, v45
	v_mov_b32_e32 v74, v46
	v_mov_b32_e32 v75, v47
	v_mov_b32_e32 v68, v48
	v_mov_b32_e32 v69, v49
	v_mov_b32_e32 v70, v50
	v_mov_b32_e32 v71, v51
	v_mov_b32_e32 v64, v52
	v_mov_b32_e32 v65, v53
	v_mov_b32_e32 v66, v54
	v_mov_b32_e32 v67, v55
	v_mov_b32_e32 v84, v56
	v_mov_b32_e32 v85, v57
	v_mov_b32_e32 v86, v58
	v_mov_b32_e32 v87, v59
	s_andn2_b64 exec, exec, s[38:39]
	s_cbranch_execz .LBB0_48

.LBB0_86:
	s_or_b64 exec, exec, s[36:37]
	v_add_f32_e32 v106, v106, v128
	v_fma_f32 v106, v106, 0.5, -v75
	v_add_f32_e32 v104, v104, v132
	v_add_f32_e32 v103, v103, v123
	v_fma_f32 v140, v28, v106, v75
	v_add_f32_e32 v106, v111, v120
	v_fma_f32 v104, v104, 0.5, -v76
	v_fma_f32 v103, v103, 0.5, -v81
	v_fma_f32 v106, v106, 0.5, -v79
	v_fma_f32 v142, v29, v104, v76
	v_add_f32_e32 v104, v107, v121
	v_fma_f32 v145, v6, v103, v81
	v_add_f32_e32 v103, v108, v126
	v_add_f32_e32 v102, v102, v129
	v_fma_f32 v111, v4, v106, v79
	v_add_f32_e32 v106, v118, v124
	v_fma_f32 v104, v104, 0.5, -v80
	v_fma_f32 v103, v103, 0.5, -v86
	v_add_f32_e32 v99, v99, v122
	v_fma_f32 v102, v102, 0.5, -v88
	v_fma_f32 v106, v106, 0.5, -v84
	v_mul_f32_e32 v141, v20, v111
	v_fma_f32 v143, v5, v104, v80
	v_fma_f32 v108, v10, v103, v86
	v_fma_f32 v99, v99, 0.5, -v82
	v_add_f32_e32 v103, v119, v37
	v_pk_add_f32 v[58:59], v[58:59], v[60:61]
	v_fma_f32 v149, v12, v102, v88
	v_add_f32_e32 v102, v109, v51
	v_fma_f32 v118, v8, v106, v84
	v_mul_f32_e32 v106, v141, v141
	v_mul_f32_e32 v144, v21, v143
	v_fma_f32 v147, v7, v99, v82
	v_add_f32_e32 v99, v105, v127
	v_fma_f32 v103, v103, 0.5, -v117
	v_fma_f32 v102, v102, 0.5, -v116
	v_pk_fma_f32 v[58:59], v[58:59], 0.5, v[52:53] op_sel_hi:[1,0,1] neg_lo:[0,0,1] neg_hi:[0,0,1]
	v_add_f32_e32 v104, v113, v125
	v_fmac_f32_e32 v106, v144, v144
	v_mul_f32_e32 v146, v22, v145
	v_fma_f32 v99, v99, 0.5, -v87
	v_fma_f32 v119, v0, v103, v117
	v_fma_f32 v109, v1, v102, v116
	v_pk_fma_f32 v[102:103], v[16:17], v[58:59], v[52:53]
	v_fma_f32 v104, v104, 0.5, -v85
	v_fmac_f32_e32 v106, v146, v146
	v_fma_f32 v148, v11, v99, v87
	v_mul_f32_e32 v99, v23, v147
	v_pk_mul_f32 v[58:59], v[24:25], v[102:103]
	v_fma_f32 v113, v9, v104, v85
	v_fmac_f32_e32 v106, v99, v99
	v_pk_mul_f32 v[104:105], v[58:59], v[58:59]
	v_pk_add_f32 v[56:57], v[56:57], v[62:63]
	v_add_f32_e32 v104, v104, v106
	v_pk_fma_f32 v[56:57], v[56:57], 0.5, v[54:55] op_sel_hi:[1,0,1] neg_lo:[0,0,1] neg_hi:[0,0,1]
	v_add_f32_e32 v150, v105, v104
	v_pk_fma_f32 v[104:105], v[18:19], v[56:57], v[54:55]
	v_add_f32_e32 v98, v98, v112
	v_pk_mul_f32 v[56:57], v[26:27], v[104:105]
	v_add_f32_e32 v65, v65, v133
	v_pk_mul_f32 v[106:107], v[56:57], v[56:57]
	v_add_f32_e32 v100, v100, v136
	v_add_f32_e32 v106, v106, v150
	v_add_f32_e32 v106, v107, v106
	s_nop 1
	v_mov_b32_dpp v107, v106 quad_perm:[1,0,3,2] row_mask:0xf bank_mask:0xf
	v_add_f32_e32 v97, v97, v139
	v_add_f32_e32 v101, v101, v110
	v_fma_f32 v98, v98, 0.5, -v114
	v_fma_f32 v65, v65, 0.5, -v92
	s_waitcnt lgkmcnt(0)
	v_add_f32_e32 v106, v106, v107
	s_nop 1
	v_mov_b32_dpp v107, v106 quad_perm:[2,3,0,1] row_mask:0xf bank_mask:0xf
	v_fma_f32 v100, v100, 0.5, -v77
	v_fma_f32 v97, v97, 0.5, -v78
	v_fma_f32 v101, v101, 0.5, -v115
	v_fma_f32 v98, v3, v98, v114
	s_waitcnt lgkmcnt(0)
	v_add_f32_e32 v106, v106, v107
	s_nop 1
	v_mov_b32_dpp v107, v106 row_shl:4 row_mask:0xf bank_mask:0x5
	v_mov_b32_dpp v107, v106 row_shr:4 row_mask:0xf bank_mask:0xa
	v_fma_f32 v100, v30, v100, v77
	v_fma_f32 v97, v31, v97, v78
	v_fma_f32 v101, v2, v101, v115
	v_add_f32_e32 v91, v91, v130
	s_waitcnt lgkmcnt(0)
	v_add_f32_e32 v106, v106, v107
	v_add_f32_e32 v106, 0x2b8cbccc, v106
	v_rsq_f32_e32 v106, v106
	v_fma_f32 v107, v15, v65, v92
	v_ashrrev_i32_e32 v65, 31, v64
	v_fma_f32 v91, v91, 0.5, -v89
	v_mul_f32_e32 v141, v141, v106
	v_mul_f32_e32 v144, v144, v106
	v_mul_f32_e32 v146, v146, v106
	v_mul_f32_e32 v150, v99, v106
	v_mul_f32_e32 v151, v58, v106
	v_mul_f32_e32 v152, v59, v106
	v_mul_f32_e32 v153, v56, v106
	v_mul_f32_e32 v106, v57, v106
	v_cvt_pk_bf16_f32 v56, v140, v142
	v_cvt_pk_bf16_f32 v57, v100, v97
	v_cvt_pk_bf16_f32 v58, v119, v109
	v_cvt_pk_bf16_f32 v59, v101, v98
	v_lshlrev_b64 v[98:99], 9, v[64:65]
	v_lshlrev_b64 v[64:65], 10, v[64:65]
	v_lshl_add_u64 v[100:101], v[40:41], 0, v[64:65]
	v_add_f32_e32 v83, v83, v131
	global_store_dwordx4 v[100:101], v[56:59], off
	v_lshl_add_u64 v[100:101], v[42:43], 0, v[64:65]
	v_fma_f32 v91, v13, v91, v89
	v_cvt_pk_bf16_f32 v56, v111, v143
	v_cvt_pk_bf16_f32 v57, v145, v147
	v_cvt_pk_bf16_f32 v58, v102, v103
	v_fma_f32 v83, v83, 0.5, -v90
	v_cvt_pk_bf16_f32 v59, v104, v105
	global_store_dwordx4 v[100:101], v[56:59], off
	v_lshl_add_u64 v[100:101], v[44:45], 0, v[64:65]
	v_fma_f32 v83, v14, v83, v90
	v_cvt_pk_bf16_f32 v56, v118, v113
	v_cvt_pk_bf16_f32 v57, v108, v148
	v_cvt_pk_bf16_f32 v58, v149, v91
	v_cvt_pk_bf16_f32 v59, v83, v107
	global_store_dwordx4 v[100:101], v[56:59], off
	v_lshl_add_u64 v[64:65], v[46:47], 0, v[64:65]
	v_add_f32_e32 v73, v73, v134
	v_cvt_pk_bf16_f32 v56, v141, v144
	v_cvt_pk_bf16_f32 v57, v146, v150
	v_cvt_pk_bf16_f32 v58, v151, v152
	v_cvt_pk_bf16_f32 v59, v153, v106
	v_fma_f32 v73, v73, 0.5, -v93
	global_store_dwordx4 v[64:65], v[56:59], off
	v_fma_f32 v73, v32, v73, v93
	v_add_f32_e32 v83, v73, v73
	v_add_f32_e32 v58, v72, v135
	v_fma_f32 v58, v58, 0.5, -v94
	v_fma_f32 v58, v33, v58, v94
	v_mul_f32_e32 v83, 0xbfb8aa3b, v83
	v_mul_f32_e32 v91, 0xbfb8aa3b, v73
	v_add_f32_e32 v59, v58, v58
	v_exp_f32_e32 v83, v83
	v_exp_f32_e32 v91, v91
	v_mul_f32_e32 v59, 0xbfb8aa3b, v59
	v_exp_f32_e32 v59, v59
	v_mul_f32_e32 v64, 0xbfb8aa3b, v58
	v_add_f32_e32 v56, 1.0, v83
	v_add_f32_e32 v57, 1.0, v91
	v_exp_f32_e32 v64, v64
	v_rcp_f32_e32 v56, v56
	v_rcp_f32_e32 v57, v57
	v_add_f32_e32 v59, 1.0, v59
	v_rcp_f32_e32 v59, v59
	v_add_f32_e32 v64, 1.0, v64
	v_fma_f32 v56, v56, 2.0, -1.0
	v_rcp_f32_e32 v64, v64
	v_cndmask_b32_e64 v57, v57, v73, s[38:39]
	v_cndmask_b32_e32 v56, v57, v56, vcc
	v_fma_f32 v57, v59, 2.0, -1.0
	v_add_f32_e32 v59, v71, v137
	v_fma_f32 v59, v59, 0.5, -v95
	v_fma_f32 v59, v34, v59, v95
	v_cndmask_b32_e64 v58, v64, v58, s[38:39]
	v_add_f32_e32 v64, v59, v59
	v_mul_f32_e32 v64, 0xbfb8aa3b, v64
	v_mul_f32_e32 v65, 0xbfb8aa3b, v59
	v_exp_f32_e32 v64, v64
	v_exp_f32_e32 v65, v65
	v_cndmask_b32_e32 v57, v58, v57, vcc
	v_cvt_pk_bf16_f32 v56, v56, v57
	v_add_f32_e32 v58, 1.0, v64
	v_add_f32_e32 v64, 1.0, v65
	v_add_f32_e32 v65, v70, v138
	v_fma_f32 v65, v65, 0.5, -v96
	v_fma_f32 v65, v35, v65, v96
	v_add_f32_e32 v70, v65, v65
	v_mul_f32_e32 v70, 0xbfb8aa3b, v70
	v_mul_f32_e32 v71, 0xbfb8aa3b, v65
	v_exp_f32_e32 v70, v70
	v_exp_f32_e32 v71, v71
	v_rcp_f32_e32 v58, v58
	v_rcp_f32_e32 v64, v64
	v_add_f32_e32 v70, 1.0, v70
	v_add_f32_e32 v71, 1.0, v71
	v_rcp_f32_e32 v70, v70
	v_rcp_f32_e32 v71, v71
	v_fma_f32 v58, v58, 2.0, -1.0
	v_cndmask_b32_e64 v59, v64, v59, s[38:39]
	v_cndmask_b32_e32 v58, v59, v58, vcc
	v_fma_f32 v59, v70, 2.0, -1.0
	v_cndmask_b32_e64 v64, v71, v65, s[38:39]
	v_cndmask_b32_e32 v59, v64, v59, vcc
	v_cvt_pk_bf16_f32 v57, v58, v59
	v_lshl_add_u64 v[58:59], v[48:49], 0, v[98:99]
	s_add_i32 s6, s6, 1
	global_store_dwordx2 v[58:59], v[56:57], off
	s_cmp_eq_u32 s6, 16
	v_mov_b32_e32 v97, v78
	v_mov_b32_e32 v100, v77
	v_mov_b32_e32 v104, v76
	v_mov_b32_e32 v106, v75
	v_mov_b32_e32 v99, v82
	v_mov_b32_e32 v103, v81
	v_mov_b32_e32 v107, v80
	v_mov_b32_e32 v111, v79
	v_mov_b32_e32 v65, v92
	v_mov_b32_e32 v83, v90
	v_mov_b32_e32 v91, v89
	v_mov_b32_e32 v102, v88
	v_mov_b32_e32 v105, v87
	v_mov_b32_e32 v108, v86
	v_mov_b32_e32 v113, v85
	v_mov_b32_e32 v118, v84
	v_mov_b32_e32 v70, v96
	v_mov_b32_e32 v71, v95
	v_mov_b32_e32 v72, v94
	v_mov_b32_e32 v73, v93
	v_mov_b32_e32 v78, v139
	v_mov_b32_e32 v77, v136
	v_mov_b32_e32 v76, v132
	v_mov_b32_e32 v75, v128
	v_mov_b32_e32 v82, v122
	v_mov_b32_e32 v81, v123
	v_mov_b32_e32 v80, v121
	v_mov_b32_e32 v79, v120
	v_mov_b32_e32 v92, v133
	v_mov_b32_e32 v90, v131
	v_mov_b32_e32 v89, v130
	v_mov_b32_e32 v88, v129
	v_mov_b32_e32 v87, v127
	v_mov_b32_e32 v86, v126
	v_mov_b32_e32 v85, v125
	v_mov_b32_e32 v84, v124
	v_mov_b32_e32 v96, v138
	v_mov_b32_e32 v95, v137
	v_mov_b32_e32 v94, v135
	v_mov_b32_e32 v93, v134
	v_mov_b32_e32 v119, v117
	v_mov_b32_e32 v109, v116
	v_mov_b32_e32 v101, v115
	v_mov_b32_e32 v98, v114
	v_mov_b64_e32 v[56:57], v[54:55]
	v_mov_b64_e32 v[58:59], v[52:53]
	s_cbranch_scc1 .LBB0_82
